# restore 8 wait states between MFMA results and their first VALU reader at 3 sites where a removed vmcnt wait had shortened the distance
# baseline (speedup 1.0000x reference)
; template <int NT, int NKK, int NDT, int MODE, bool MASK> ...
;     ...
;     for (int jh = 0; jh < NT / JB; ++jh) {
;       int oz = 0; if (NT > JB) asm volatile("" : "+v"(oz));
;       f32x4 s[JB][2];
;       __builtin_amdgcn_s_setprio(1);
; #pragma unroll
;       for (int t = 0; t < 2; ++t)
; #pragma unroll
;         for (int kk = 0; kk < NKK; ++kk) {
;           const bf16x8 kf = *(LAS const bf16x8*)(Kl + oz + (32 * st + 16 * t + r) * KSTR + (32 * kk + 8 * lg) * 2);
; #pragma unroll
;           for (int jj = 0; jj < JB; ++jj) s[jj][t] = mfma16(kf, qf[jh * JB + jj][kk], kk == 0 ? (f32x4){0.f, 0.f, 0.f, 0.f} : s[jj][t]);
;         }
;       __builtin_amdgcn_s_setprio(0);
;       bf16x8 pf[JB];
;       if (NT > JB) __builtin_amdgcn_sched_barrier(0);
; #pragma unroll
;       for (int jj = 0; jj < JB; ++jj) {
;         const int j = jh * JB + jj;
;         float mx = -INFINITY;
; #pragma unroll
;         for (int t = 0; t < 2; ++t)
; #pragma unroll
;           for (int i = 0; i < 4; ++i) {
;             if (MASK) { const int kp = kpos0 + 32 * st + 16 * t + 4 * lg + i; if (!mask_ok<MODE>(tq[j], kp, W)) s[jj][t][i] = -INFINITY; }
;             mx = fmaxf(mx, s[jj][t][i]);
;           }
;         mx = max_x16_x32(mx);
;         if (NT > 2 || __any(mx > m[j] + 8.0f / c)) {
;           const float mnew = fmaxf(m[j], mx);
;           const float ms2 = (mnew == -INFINITY) ? 0.f : mnew;
;           const float alpha = ex2((m[j] - ms2) * c);
;           m[j] = mnew; l[j] *= alpha;
; #pragma unroll
;           for (int dt = 0; dt < NDT; ++dt) o[j][dt] *= alpha;
;         }
;         const float mc = ((m[j] == -INFINITY) ? 0.f : m[j]) * c;
;         float p0[4], p1[4], ps = 0.f;
; #pragma unroll
;         for (int i = 0; i < 4; ++i) { p0[i] = ex2(s[jj][0][i] * c - mc); p1[i] = ex2(s[jj][1][i] * c - mc); ps += p0[i] + p1[i]; }
;         l[j] += ps;
;         pf[jj] = pack8(p0, p1);
;       }
;       if (NT > JB) __builtin_amdgcn_sched_barrier(0);
;       __builtin_amdgcn_s_setprio(1);
; #pragma unroll
;       for (int dt = 0; dt < NDT; ++dt) {
;         const s16x4 v0 = ds_tr(Vl + oz + (32 * st + 4 * lg + vq) * VSTR + (16 * dt + 4 * vp) * 2);
;         const s16x4 v1 = ds_tr(Vl + oz + (32 * st + 16 + 4 * lg + vq) * VSTR + (16 * dt + 4 * vp) * 2);
;         const bf16x8 vf = (bf16x8){v0[0], v0[1], v0[2], v0[3], v1[0], v1[1], v1[2], v1[3]};
; #pragma unroll
.LBB0_1126:
	v_mov_b32_e32 v196, v206
	v_mov_b32_e32 v232, v209
	v_or_b32_e32 v199, s8, v203
	v_mov_b32_e32 v206, s45
	v_mov_b32_e32 v209, 0
	v_mov_b32_e32 v197, v207
	v_mov_b32_e32 v235, v210
	v_or_b32_e32 v198, s8, v201
	v_mad_u32_u24 v208, v199, s80, v206
	s_setprio 1
	v_mul_u32_u24_e32 v244, 0x90, v198
	v_add3_u32 v198, v1, v209, v244
	ds_read_b128 v[210:213], v198
	ds_read_b128 v[214:217], v198 offset:64
	s_waitcnt lgkmcnt(1)
	v_mfma_f32_16x16x32_bf16 v[218:221], v[210:213], v[2:5], 0
	v_mfma_f32_16x16x32_bf16 v[210:213], v[210:213], v[10:13], 0
	s_waitcnt lgkmcnt(0)
	v_mfma_f32_16x16x32_bf16 v[218:221], v[214:217], v[6:9], v[218:221]
	v_mfma_f32_16x16x32_bf16 v[210:213], v[214:217], v[14:17], v[210:213]
	ds_read_b128 v[214:217], v198 offset:2304
	ds_read_b128 v[222:225], v198 offset:2368
	s_waitcnt lgkmcnt(1)
	v_mfma_f32_16x16x32_bf16 v[228:231], v[214:217], v[2:5], 0
	v_mfma_f32_16x16x32_bf16 v[214:217], v[214:217], v[10:13], 0
	s_waitcnt lgkmcnt(0)
	v_mfma_f32_16x16x32_bf16 v[228:231], v[222:225], v[6:9], v[228:231]
	v_mfma_f32_16x16x32_bf16 v[214:217], v[222:225], v[14:17], v[214:217]
	s_setprio 0
	v_max3_f32 v198, v218, s81, v219
	v_max3_f32 v198, v198, v220, v221
	s_nop 3
	v_max3_f32 v198, v198, v228, v229
	v_max3_f32 v198, v198, v230, v231
	v_mov_b32_e32 v199, v198
	s_nop 1
	v_permlane16_swap_b32_e32 v198, v199
	v_max_f32_e32 v198, v198, v199
	v_mov_b32_e32 v199, v198
	s_nop 1
	v_permlane32_swap_b32_e32 v198, v199
	v_max3_f32 v206, v196, v198, v199
	v_cmp_eq_f32_e32 vcc, s81, v206
	s_nop 1
	v_cndmask_b32_e64 v198, v206, 0, vcc
	v_sub_f32_e32 v196, v196, v198
	v_mul_f32_e32 v198, 0x3e38aa3b, v206
	v_cndmask_b32_e64 v198, v198, 0, vcc
	v_fma_f32 v207, v228, s42, -v198
	v_exp_f32_e32 v223, v207
	v_fma_f32 v207, v219, s42, -v198
	v_exp_f32_e32 v225, v207
	v_fma_f32 v207, v229, s42, -v198
	v_exp_f32_e32 v229, v207
	v_fma_f32 v207, v220, s42, -v198
	v_exp_f32_e32 v237, v207
	v_fma_f32 v207, v230, s42, -v198
	v_fma_f32 v199, v218, s42, -v198
	v_exp_f32_e32 v239, v207
	v_fma_f32 v207, v221, s42, -v198
	v_fma_f32 v198, v231, s42, -v198
	v_exp_f32_e32 v231, v198
	v_max3_f32 v198, v210, s81, v211
	v_max3_f32 v198, v198, v212, v213
	v_max3_f32 v198, v198, v214, v215
	v_max3_f32 v198, v198, v216, v217
	v_exp_f32_e32 v241, v207
	v_mov_b32_e32 v207, v198
	s_nop 1
	v_permlane16_swap_b32_e32 v198, v207
	v_max_f32_e32 v198, v198, v207
	v_mul_f32_e32 v196, 0x3e38aa3b, v196
	v_mov_b32_e32 v207, v198
	v_exp_f32_e32 v196, v196
	s_nop 0
	v_permlane32_swap_b32_e32 v198, v207
	v_max3_f32 v207, v197, v198, v207
	v_cmp_eq_f32_e32 vcc, s81, v207
	v_pk_mul_f32 v[140:141], v[140:141], v[196:197] op_sel_hi:[1,0]
	v_pk_mul_f32 v[138:139], v[138:139], v[196:197] op_sel_hi:[1,0]
	v_cndmask_b32_e64 v198, v207, 0, vcc
	v_pk_mul_f32 v[136:137], v[136:137], v[196:197] op_sel_hi:[1,0]
	v_pk_mul_f32 v[134:135], v[134:135], v[196:197] op_sel_hi:[1,0]
	v_pk_mul_f32 v[156:157], v[156:157], v[196:197] op_sel_hi:[1,0]
	v_pk_mul_f32 v[154:155], v[154:155], v[196:197] op_sel_hi:[1,0]
	v_pk_mul_f32 v[164:165], v[164:165], v[196:197] op_sel_hi:[1,0]
	v_pk_mul_f32 v[162:163], v[162:163], v[196:197] op_sel_hi:[1,0]
	v_sub_f32_e32 v197, v197, v198
	v_mul_f32_e32 v197, 0x3e38aa3b, v197
	v_exp_f32_e32 v242, v197
	v_mul_f32_e32 v197, 0x3e38aa3b, v207
	v_cndmask_b32_e64 v197, v197, 0, vcc
	v_fma_f32 v198, v210, s42, -v197
	v_fma_f32 v210, v214, s42, -v197
	v_exp_f32_e32 v222, v210
	v_fma_f32 v210, v211, s42, -v197
	v_exp_f32_e32 v224, v210
	v_fma_f32 v210, v215, s42, -v197
	v_exp_f32_e32 v199, v199
	v_exp_f32_e32 v198, v198
	v_exp_f32_e32 v228, v210
	v_fma_f32 v210, v212, s42, -v197
	v_exp_f32_e32 v236, v210
	v_fma_f32 v210, v216, s42, -v197
	v_exp_f32_e32 v238, v210
	v_fma_f32 v210, v213, s42, -v197
	v_fma_f32 v197, v217, s42, -v197
	v_exp_f32_e32 v240, v210
	v_exp_f32_e32 v230, v197
	v_pk_mul_f32 v[112:113], v[112:113], v[242:243] op_sel_hi:[1,0]
	v_pk_mul_f32 v[110:111], v[110:111], v[242:243] op_sel_hi:[1,0]
	v_pk_mul_f32 v[108:109], v[108:109], v[242:243] op_sel_hi:[1,0]
	v_pk_mul_f32 v[106:107], v[106:107], v[242:243] op_sel_hi:[1,0]
	v_pk_mul_f32 v[124:125], v[124:125], v[242:243] op_sel_hi:[1,0]
	v_pk_mul_f32 v[122:123], v[122:123], v[242:243] op_sel_hi:[1,0]
	v_pk_mul_f32 v[132:133], v[132:133], v[242:243] op_sel_hi:[1,0]
	v_pk_mul_f32 v[130:131], v[130:131], v[242:243] op_sel_hi:[1,0]
	v_mov_b32_e32 v243, v196
	v_pk_add_f32 v[196:197], v[198:199], v[222:223]
	v_pk_add_f32 v[210:211], v[224:225], v[228:229]
	v_cvt_pk_bf16_f32 v218, v199, v225
	v_pk_add_f32 v[196:197], v[210:211], v[196:197]
	v_pk_add_f32 v[210:211], v[236:237], v[238:239]
	v_cvt_pk_bf16_f32 v219, v237, v241
	v_pk_add_f32 v[196:197], v[210:211], v[196:197]
	v_pk_add_f32 v[210:211], v[240:241], v[230:231]
	v_cvt_pk_bf16_f32 v220, v223, v229
	v_pk_add_f32 v[196:197], v[210:211], v[196:197]
	v_cvt_pk_bf16_f32 v210, v198, v224
	v_pk_fma_f32 v[180:181], v[180:181], v[242:243], v[196:197]
	v_cvt_pk_bf16_f32 v221, v239, v231
	v_cvt_pk_bf16_f32 v211, v236, v240
	v_cvt_pk_bf16_f32 v212, v222, v228
	v_cvt_pk_bf16_f32 v213, v238, v230
	s_setprio 1
	v_add3_u32 v196, v208, v209, v204
	ds_read_b64_tr_b16 v[216:217], v196 offset:11776
	ds_read_b64_tr_b16 v[214:215], v196 offset:9216
	ds_read_b64_tr_b16 v[222:223], v196 offset:9248
	ds_read_b64_tr_b16 v[224:225], v196 offset:11808
	s_waitcnt lgkmcnt(2)
	v_mfma_f32_16x16x32_bf16 v[138:141], v[214:217], v[218:221], v[138:141]
	v_mfma_f32_16x16x32_bf16 v[110:113], v[214:217], v[210:213], v[110:113]
	ds_read_b64_tr_b16 v[214:215], v196 offset:9280
	ds_read_b64_tr_b16 v[216:217], v196 offset:11840
	s_waitcnt lgkmcnt(0)
; template <int NT, int NKK, int NDT, int MODE, bool MASK> ...
;     ...
;     for (int jh = 0; jh < NT / JB; ++jh) {
;       int oz = 0; if (NT > JB) asm volatile("" : "+v"(oz));
;       f32x4 s[JB][2];
;       __builtin_amdgcn_s_setprio(1);
; #pragma unroll
;       for (int t = 0; t < 2; ++t)
; #pragma unroll
;         for (int kk = 0; kk < NKK; ++kk) {
;           const bf16x8 kf = *(LAS const bf16x8*)(Kl + oz + (32 * st + 16 * t + r) * KSTR + (32 * kk + 8 * lg) * 2);
; #pragma unroll
;           for (int jj = 0; jj < JB; ++jj) s[jj][t] = mfma16(kf, qf[jh * JB + jj][kk], kk == 0 ? (f32x4){0.f, 0.f, 0.f, 0.f} : s[jj][t]);
;         }
;       __builtin_amdgcn_s_setprio(0);
;       bf16x8 pf[JB];
;       if (NT > JB) __builtin_amdgcn_sched_barrier(0);
; #pragma unroll
;       for (int jj = 0; jj < JB; ++jj) {
;         const int j = jh * JB + jj;
;         float mx = -INFINITY;
; #pragma unroll
;         for (int t = 0; t < 2; ++t)
; #pragma unroll
;           for (int i = 0; i < 4; ++i) {
;             if (MASK) { const int kp = kpos0 + 32 * st + 16 * t + 4 * lg + i; if (!mask_ok<MODE>(tq[j], kp, W)) s[jj][t][i] = -INFINITY; }
;             mx = fmaxf(mx, s[jj][t][i]);
;           }
;         mx = max_x16_x32(mx);
;         if (NT > 2 || __any(mx > m[j] + 8.0f / c)) {
;           const float mnew = fmaxf(m[j], mx);
;           const float ms2 = (mnew == -INFINITY) ? 0.f : mnew;
;           const float alpha = ex2((m[j] - ms2) * c);
;           m[j] = mnew; l[j] *= alpha;
; #pragma unroll
;           for (int dt = 0; dt < NDT; ++dt) o[j][dt] *= alpha;
;         }
;         const float mc = ((m[j] == -INFINITY) ? 0.f : m[j]) * c;
;         float p0[4], p1[4], ps = 0.f;
; #pragma unroll
;         for (int i = 0; i < 4; ++i) { p0[i] = ex2(s[jj][0][i] * c - mc); p1[i] = ex2(s[jj][1][i] * c - mc); ps += p0[i] + p1[i]; }
;         l[j] += ps;
;         pf[jj] = pack8(p0, p1);
;       }
;       if (NT > JB) __builtin_amdgcn_sched_barrier(0);
;       __builtin_amdgcn_s_setprio(1);
; #pragma unroll
;       for (int dt = 0; dt < NDT; ++dt) {
;         const s16x4 v0 = ds_tr(Vl + oz + (32 * st + 4 * lg + vq) * VSTR + (16 * dt + 4 * vp) * 2);
;         const s16x4 v1 = ds_tr(Vl + oz + (32 * st + 16 + 4 * lg + vq) * VSTR + (16 * dt + 4 * vp) * 2);
;         const bf16x8 vf = (bf16x8){v0[0], v0[1], v0[2], v0[3], v1[0], v1[1], v1[2], v1[3]};
; #pragma unroll
	v_mfma_f32_16x16x32_bf16 v[154:157], v[214:217], v[218:221], v[154:157]
	v_mfma_f32_16x16x32_bf16 v[122:125], v[214:217], v[210:213], v[122:125]
	ds_read_b64_tr_b16 v[214:215], v196 offset:9312
	ds_read_b64_tr_b16 v[216:217], v196 offset:11872
	v_mfma_f32_16x16x32_bf16 v[134:137], v[222:225], v[218:221], v[134:137]
	v_mfma_f32_16x16x32_bf16 v[106:109], v[222:225], v[210:213], v[106:109]
	s_waitcnt lgkmcnt(0)
	v_mfma_f32_16x16x32_bf16 v[162:165], v[214:217], v[218:221], v[162:165]
	v_mfma_f32_16x16x32_bf16 v[130:133], v[214:217], v[210:213], v[130:133]
	s_setprio 0
	v_mov_b32_e32 v246, 0
	s_setprio 1
	v_add3_u32 v196, v1, v246, v244
	ds_read_b128 v[210:213], v196
	ds_read_b128 v[214:217], v196 offset:64
	ds_read_b128 v[222:225], v196 offset:2304
	ds_read_b128 v[228:231], v196 offset:2368
	s_waitcnt lgkmcnt(3)
	v_mfma_f32_16x16x32_bf16 v[218:221], v[210:213], v[18:21], 0
	v_mfma_f32_16x16x32_bf16 v[210:213], v[210:213], v[26:29], 0
	s_waitcnt lgkmcnt(1)
	v_mfma_f32_16x16x32_bf16 v[236:239], v[222:225], v[18:21], 0
	v_mfma_f32_16x16x32_bf16 v[222:225], v[222:225], v[26:29], 0
	v_mfma_f32_16x16x32_bf16 v[218:221], v[214:217], v[22:25], v[218:221]
	v_mfma_f32_16x16x32_bf16 v[212:215], v[214:217], v[30:33], v[210:213]
	s_waitcnt lgkmcnt(0)
	v_mfma_f32_16x16x32_bf16 v[236:239], v[228:231], v[22:25], v[236:239]
	v_mfma_f32_16x16x32_bf16 v[222:225], v[228:231], v[30:33], v[222:225]
	s_setprio 0
	s_nop 1
	s_nop 0
	v_max3_f32 v196, v218, s81, v219
	v_max3_f32 v196, v196, v220, v221
	s_nop 1
	v_max3_f32 v196, v196, v236, v237
	v_max3_f32 v196, v196, v238, v239
	v_mov_b32_e32 v197, v196
	s_nop 1
	v_permlane16_swap_b32_e32 v196, v197
	v_max_f32_e32 v196, v196, v197
	v_mov_b32_e32 v197, v196
	s_nop 1
	v_permlane32_swap_b32_e32 v196, v197
	v_max3_f32 v209, v232, v196, v197
	v_cmp_eq_f32_e32 vcc, s81, v209
	s_nop 1
	v_cndmask_b32_e64 v196, v209, 0, vcc
	v_sub_f32_e32 v196, v232, v196
	v_mul_f32_e32 v196, 0x3e38aa3b, v196
	v_exp_f32_e32 v196, v196
	s_nop 0
	v_pk_mul_f32 v[152:153], v[152:153], v[196:197] op_sel_hi:[1,0]
	v_pk_mul_f32 v[150:151], v[150:151], v[196:197] op_sel_hi:[1,0]
	v_pk_mul_f32 v[148:149], v[148:149], v[196:197] op_sel_hi:[1,0]
	v_pk_mul_f32 v[146:147], v[146:147], v[196:197] op_sel_hi:[1,0]
	v_pk_mul_f32 v[160:161], v[160:161], v[196:197] op_sel_hi:[1,0]
	v_pk_mul_f32 v[158:159], v[158:159], v[196:197] op_sel_hi:[1,0]
	v_pk_mul_f32 v[168:169], v[168:169], v[196:197] op_sel_hi:[1,0]
	v_pk_mul_f32 v[166:167], v[166:167], v[196:197] op_sel_hi:[1,0]
	v_mul_f32_e32 v197, 0x3e38aa3b, v209
	v_cndmask_b32_e64 v197, v197, 0, vcc
	v_fma_f32 v198, v218, s42, -v197
	v_exp_f32_e32 v199, v198
	v_fma_f32 v198, v236, s42, -v197
	v_exp_f32_e32 v229, v198
	v_fma_f32 v198, v219, s42, -v197
	v_exp_f32_e32 v231, v198
	v_fma_f32 v198, v237, s42, -v197
	v_exp_f32_e32 v237, v198
	v_fma_f32 v198, v220, s42, -v197
	v_exp_f32_e32 v241, v198
	v_fma_f32 v198, v238, s42, -v197
	v_exp_f32_e32 v243, v198
	v_fma_f32 v198, v221, s42, -v197
	v_fma_f32 v197, v239, s42, -v197
	v_exp_f32_e32 v239, v197
	v_max3_f32 v197, v212, s81, v213
	v_max3_f32 v197, v197, v214, v215
	v_max3_f32 v197, v197, v222, v223
	v_max3_f32 v197, v197, v224, v225
	v_exp_f32_e32 v221, v198
	v_mov_b32_e32 v198, v197
	s_nop 1
	v_permlane16_swap_b32_e32 v197, v198
	v_max_f32_e32 v197, v197, v198
	v_mov_b32_e32 v198, v197
	s_nop 1
	v_permlane32_swap_b32_e32 v197, v198
	v_max3_f32 v210, v235, v197, v198
	v_cmp_eq_f32_e32 vcc, s81, v210
	v_cvt_pk_bf16_f32 v216, v199, v231
	v_cvt_pk_bf16_f32 v217, v241, v221
	v_cndmask_b32_e64 v197, v210, 0, vcc
	v_sub_f32_e32 v197, v235, v197
	v_mul_f32_e32 v197, 0x3e38aa3b, v197
	v_exp_f32_e32 v244, v197
	v_mul_f32_e32 v197, 0x3e38aa3b, v210
	v_cndmask_b32_e64 v197, v197, 0, vcc
	v_fma_f32 v211, v222, s42, -v197
	v_exp_f32_e32 v228, v211
	v_fma_f32 v211, v213, s42, -v197
	v_fma_f32 v198, v212, s42, -v197
	v_exp_f32_e32 v230, v211
	v_fma_f32 v211, v223, s42, -v197
	v_exp_f32_e32 v198, v198
	v_exp_f32_e32 v236, v211
	v_fma_f32 v211, v214, s42, -v197
	v_exp_f32_e32 v240, v211
	v_fma_f32 v211, v224, s42, -v197
	v_exp_f32_e32 v242, v211
	v_fma_f32 v211, v215, s42, -v197
	v_fma_f32 v197, v225, s42, -v197
	v_exp_f32_e32 v220, v211
	v_exp_f32_e32 v238, v197
	v_pk_mul_f32 v[120:121], v[120:121], v[244:245] op_sel_hi:[1,0]
	v_pk_mul_f32 v[118:119], v[118:119], v[244:245] op_sel_hi:[1,0]
	v_pk_mul_f32 v[116:117], v[116:117], v[244:245] op_sel_hi:[1,0]
	v_pk_mul_f32 v[114:115], v[114:115], v[244:245] op_sel_hi:[1,0]
	v_pk_mul_f32 v[128:129], v[128:129], v[244:245] op_sel_hi:[1,0]
	v_pk_mul_f32 v[126:127], v[126:127], v[244:245] op_sel_hi:[1,0]
	v_pk_mul_f32 v[144:145], v[144:145], v[244:245] op_sel_hi:[1,0]
	v_pk_mul_f32 v[142:143], v[142:143], v[244:245] op_sel_hi:[1,0]
	v_mov_b32_e32 v245, v196
	v_pk_add_f32 v[196:197], v[198:199], v[228:229]
	v_pk_add_f32 v[212:213], v[230:231], v[236:237]
	v_cvt_pk_bf16_f32 v218, v229, v237
	v_pk_add_f32 v[196:197], v[212:213], v[196:197]
	v_pk_add_f32 v[212:213], v[240:241], v[242:243]
	v_cvt_pk_bf16_f32 v219, v243, v239
	v_pk_add_f32 v[196:197], v[212:213], v[196:197]
	v_pk_add_f32 v[212:213], v[220:221], v[238:239]
	v_cvt_pk_bf16_f32 v214, v228, v236
	v_pk_add_f32 v[196:197], v[212:213], v[196:197]
	v_cvt_pk_bf16_f32 v212, v198, v230
	v_pk_fma_f32 v[182:183], v[182:183], v[244:245], v[196:197]
	v_cvt_pk_bf16_f32 v213, v240, v220
	v_cvt_pk_bf16_f32 v215, v242, v238
	s_setprio 1
	v_add3_u32 v196, v208, v246, v204
	ds_read_b64_tr_b16 v[222:223], v196 offset:11776
	ds_read_b64_tr_b16 v[220:221], v196 offset:9216
	ds_read_b64_tr_b16 v[228:229], v196 offset:9248
	ds_read_b64_tr_b16 v[230:231], v196 offset:11808
	s_waitcnt lgkmcnt(2)
	v_mfma_f32_16x16x32_bf16 v[150:153], v[220:223], v[216:219], v[150:153]
	v_mfma_f32_16x16x32_bf16 v[118:121], v[220:223], v[212:215], v[118:121]
	ds_read_b64_tr_b16 v[220:221], v196 offset:9280
	ds_read_b64_tr_b16 v[222:223], v196 offset:11840
	s_waitcnt lgkmcnt(0)
	v_mfma_f32_16x16x32_bf16 v[158:161], v[220:223], v[216:219], v[158:161]
	v_mfma_f32_16x16x32_bf16 v[126:129], v[220:223], v[212:215], v[126:129]
	ds_read_b64_tr_b16 v[220:221], v196 offset:9312
	ds_read_b64_tr_b16 v[222:223], v196 offset:11872
	v_mfma_f32_16x16x32_bf16 v[146:149], v[228:231], v[216:219], v[146:149]
	v_mfma_f32_16x16x32_bf16 v[114:117], v[228:231], v[212:215], v[114:117]
	s_waitcnt lgkmcnt(0)
	v_mfma_f32_16x16x32_bf16 v[166:169], v[220:223], v[216:219], v[166:169]
	v_mfma_f32_16x16x32_bf16 v[142:145], v[220:223], v[212:215], v[142:145]
	s_setprio 0
	s_mov_b32 s8, 32
	s_andn2_b64 vcc, exec, s[26:27]
	s_mov_b64 s[26:27], 0
	s_cbranch_vccz .LBB0_1126

; template <int NT, int NKK, int NDT, int MODE, bool MASK> ...
;     ...
;     for (int jh = 0; jh < NT / JB; ++jh) {
;       int oz = 0; if (NT > JB) asm volatile("" : "+v"(oz));
;       f32x4 s[JB][2];
;       __builtin_amdgcn_s_setprio(1);
; #pragma unroll
;       for (int t = 0; t < 2; ++t)
; #pragma unroll
;         for (int kk = 0; kk < NKK; ++kk) {
;           const bf16x8 kf = *(LAS const bf16x8*)(Kl + oz + (32 * st + 16 * t + r) * KSTR + (32 * kk + 8 * lg) * 2);
; #pragma unroll
;           for (int jj = 0; jj < JB; ++jj) s[jj][t] = mfma16(kf, qf[jh * JB + jj][kk], kk == 0 ? (f32x4){0.f, 0.f, 0.f, 0.f} : s[jj][t]);
;         }
;       __builtin_amdgcn_s_setprio(0);
;       bf16x8 pf[JB];
;       if (NT > JB) __builtin_amdgcn_sched_barrier(0);
; #pragma unroll
;       for (int jj = 0; jj < JB; ++jj) {
;         const int j = jh * JB + jj;
;         float mx = -INFINITY;
; #pragma unroll
;         for (int t = 0; t < 2; ++t)
; #pragma unroll
;           for (int i = 0; i < 4; ++i) {
;             if (MASK) { const int kp = kpos0 + 32 * st + 16 * t + 4 * lg + i; if (!mask_ok<MODE>(tq[j], kp, W)) s[jj][t][i] = -INFINITY; }
;             mx = fmaxf(mx, s[jj][t][i]);
;           }
;         mx = max_x16_x32(mx);
;         if (NT > 2 || __any(mx > m[j] + 8.0f / c)) {
;           const float mnew = fmaxf(m[j], mx);
;           const float ms2 = (mnew == -INFINITY) ? 0.f : mnew;
;           const float alpha = ex2((m[j] - ms2) * c);
;           m[j] = mnew; l[j] *= alpha;
; #pragma unroll
;           for (int dt = 0; dt < NDT; ++dt) o[j][dt] *= alpha;
;         }
;         const float mc = ((m[j] == -INFINITY) ? 0.f : m[j]) * c;
;         float p0[4], p1[4], ps = 0.f;
; #pragma unroll
;         for (int i = 0; i < 4; ++i) { p0[i] = ex2(s[jj][0][i] * c - mc); p1[i] = ex2(s[jj][1][i] * c - mc); ps += p0[i] + p1[i]; }
;         l[j] += ps;
;         pf[jj] = pack8(p0, p1);
;       }
;       if (NT > JB) __builtin_amdgcn_sched_barrier(0);
;       __builtin_amdgcn_s_setprio(1);
; #pragma unroll
;       for (int dt = 0; dt < NDT; ++dt) {
;         const s16x4 v0 = ds_tr(Vl + oz + (32 * st + 4 * lg + vq) * VSTR + (16 * dt + 4 * vp) * 2);
;         const s16x4 v1 = ds_tr(Vl + oz + (32 * st + 16 + 4 * lg + vq) * VSTR + (16 * dt + 4 * vp) * 2);
;         const bf16x8 vf = (bf16x8){v0[0], v0[1], v0[2], v0[3], v1[0], v1[1], v1[2], v1[3]};
; #pragma unroll
.LBB0_1265:
	v_mov_b32_e32 v197, v1
	v_or_b32_e32 v1, s8, v183
	v_or_b32_e32 v196, s8, v204
	v_mov_b32_e32 v246, 0
	v_mov_b32_e32 v199, v212
	v_mov_b32_e32 v232, v214
	v_mov_b32_e32 v235, v215
	v_or_b32_e32 v198, s8, v211
	v_mad_u32_u24 v213, v196, s80, 0
	s_setprio 1
	v_mul_u32_u24_e32 v247, 0x90, v1
	v_add3_u32 v1, v207, v246, v247
	ds_read_b128 v[214:217], v1
	ds_read_b128 v[218:221], v1 offset:64
	s_waitcnt lgkmcnt(1)
	v_mfma_f32_16x16x32_bf16 v[222:225], v[214:217], v[12:15], 0
	v_mfma_f32_16x16x32_bf16 v[214:217], v[214:217], v[20:23], 0
	s_waitcnt lgkmcnt(0)
	v_mfma_f32_16x16x32_bf16 v[222:225], v[218:221], v[16:19], v[222:225]
	v_mfma_f32_16x16x32_bf16 v[214:217], v[218:221], v[24:27], v[214:217]
	ds_read_b128 v[218:221], v1 offset:2304
	ds_read_b128 v[228:231], v1 offset:2368
	s_waitcnt lgkmcnt(1)
	v_mfma_f32_16x16x32_bf16 v[236:239], v[218:221], v[12:15], 0
	v_mfma_f32_16x16x32_bf16 v[218:221], v[218:221], v[20:23], 0
	s_waitcnt lgkmcnt(0)
	v_mfma_f32_16x16x32_bf16 v[236:239], v[228:231], v[16:19], v[236:239]
	v_mfma_f32_16x16x32_bf16 v[218:221], v[228:231], v[24:27], v[218:221]
	s_setprio 0
	v_cmp_le_i32_e32 vcc, v198, v182
	v_cmp_gt_i32_e64 s[12:13], v198, v208
	v_mov_b32_e32 v196, s81
	s_and_b64 vcc, vcc, s[12:13]
	v_cndmask_b32_e32 v212, v196, v222, vcc
	v_cmp_lt_i32_e64 s[12:13], v198, v182
	v_cmp_ge_i32_e64 s[14:15], v198, v208
	v_or_b32_e32 v196, 2, v198
	s_and_b64 s[12:13], s[12:13], s[14:15]
	v_cmp_le_i32_e64 s[14:15], v196, v182
	v_cmp_gt_i32_e64 s[16:17], v196, v208
	v_or_b32_e32 v196, 3, v198
	s_and_b64 s[14:15], s[14:15], s[16:17]
	v_cmp_le_i32_e64 s[16:17], v196, v182
	v_cmp_gt_i32_e64 s[18:19], v196, v208
	s_and_b64 s[16:17], s[16:17], s[18:19]
	v_or_b32_e32 v196, 16, v198
	v_cndmask_b32_e64 v222, v200, v223, s[12:13]
	v_cndmask_b32_e64 v223, v200, v224, s[14:15]
	v_cndmask_b32_e64 v224, v200, v225, s[16:17]
	v_cmp_le_i32_e64 s[18:19], v196, v182
	v_cmp_gt_i32_e64 s[20:21], v196, v208
	v_or_b32_e32 v225, 17, v198
	s_and_b64 s[18:19], s[18:19], s[20:21]
	v_cmp_le_i32_e64 s[20:21], v225, v182
	v_cmp_gt_i32_e64 s[22:23], v225, v208
	v_or_b32_e32 v228, 18, v198
	s_and_b64 s[20:21], s[20:21], s[22:23]
	v_cmp_le_i32_e64 s[22:23], v228, v182
	v_cmp_gt_i32_e64 s[24:25], v228, v208
	v_or_b32_e32 v198, 19, v198
	v_max3_f32 v1, v212, s81, v222
	v_mov_b32_e32 v196, s81
	s_and_b64 s[22:23], s[22:23], s[24:25]
	v_cmp_le_i32_e64 s[24:25], v198, v182
	v_cmp_gt_i32_e64 s[28:29], v198, v208
	v_max3_f32 v1, v1, v223, v224
	v_cndmask_b32_e64 v196, v196, v236, s[18:19]
	v_cndmask_b32_e64 v225, v200, v237, s[20:21]
	s_and_b64 s[24:25], s[24:25], s[28:29]
	v_max3_f32 v1, v1, v196, v225
	v_cndmask_b32_e64 v228, v200, v238, s[22:23]
	v_cndmask_b32_e64 v230, v200, v239, s[24:25]
	v_max3_f32 v1, v1, v228, v230
	v_mov_b32_e32 v198, v1
	s_nop 1
	v_permlane16_swap_b32_e32 v1, v198
	v_max_f32_e32 v1, v1, v198
	v_mov_b32_e32 v198, v1
	s_nop 1
	v_permlane32_swap_b32_e32 v1, v198
	v_max3_f32 v1, v197, v1, v198
	v_cmp_eq_f32_e64 s[28:29], s81, v1
	v_cndmask_b32_e64 v215, v200, v215, s[12:13]
	v_cndmask_b32_e64 v238, v200, v216, s[14:15]
	v_cndmask_b32_e64 v198, v1, 0, s[28:29]
	v_sub_f32_e32 v197, v197, v198
	v_mul_f32_e32 v197, 0x3e38aa3b, v197
	v_exp_f32_e32 v198, v197
	v_mul_f32_e32 v197, 0x3e38aa3b, v1
	v_cndmask_b32_e64 v236, v197, 0, s[28:29]
	v_fma_f32 v196, v196, s42, -v236
	v_exp_f32_e32 v229, v196
	v_fma_f32 v196, v222, s42, -v236
	v_exp_f32_e32 v231, v196
	v_fma_f32 v196, v225, s42, -v236
	v_exp_f32_e32 v237, v196
	v_fma_f32 v196, v223, s42, -v236
	v_exp_f32_e32 v239, v196
	v_fma_f32 v196, v228, s42, -v236
	v_exp_f32_e32 v241, v196
	v_fma_f32 v196, v224, s42, -v236
	v_exp_f32_e32 v243, v196
	v_fma_f32 v196, v230, s42, -v236
	v_exp_f32_e32 v245, v196
	v_mov_b32_e32 v196, s81
	v_cndmask_b32_e32 v228, v196, v214, vcc
	v_max3_f32 v196, v228, s81, v215
	v_cndmask_b32_e64 v242, v200, v217, s[16:17]
	v_fma_f32 v197, v212, s42, -v236
	v_max3_f32 v212, v196, v238, v242
	v_mov_b32_e32 v196, s81
	v_cndmask_b32_e64 v216, v196, v218, s[18:19]
	v_cndmask_b32_e64 v217, v200, v219, s[20:21]
	v_max3_f32 v196, v212, v216, v217
	v_cndmask_b32_e64 v220, v200, v220, s[22:23]
	v_cndmask_b32_e64 v221, v200, v221, s[24:25]
	v_max3_f32 v196, v196, v220, v221
	v_mov_b32_e32 v212, v196
	s_nop 1
	v_permlane16_swap_b32_e32 v196, v212
	v_max_f32_e32 v196, v196, v212
	v_mov_b32_e32 v212, v196
	s_nop 1
	v_permlane32_swap_b32_e32 v196, v212
	v_max3_f32 v212, v199, v196, v212
	v_cmp_eq_f32_e64 s[28:29], s81, v212
	v_pk_mul_f32 v[154:155], v[154:155], v[198:199] op_sel_hi:[1,0]
	v_pk_mul_f32 v[152:153], v[152:153], v[198:199] op_sel_hi:[1,0]
	v_cndmask_b32_e64 v196, v212, 0, s[28:29]
	v_sub_f32_e32 v196, v199, v196
	v_mul_f32_e32 v196, 0x3e38aa3b, v196
	v_exp_f32_e32 v214, v196
	v_mul_f32_e32 v196, 0x3e38aa3b, v212
	v_pk_mul_f32 v[150:151], v[150:151], v[198:199] op_sel_hi:[1,0]
	v_pk_mul_f32 v[148:149], v[148:149], v[198:199] op_sel_hi:[1,0]
	v_pk_mul_f32 v[166:167], v[166:167], v[198:199] op_sel_hi:[1,0]
	v_pk_mul_f32 v[164:165], v[164:165], v[198:199] op_sel_hi:[1,0]
	v_pk_mul_f32 v[174:175], v[174:175], v[198:199] op_sel_hi:[1,0]
	v_pk_mul_f32 v[172:173], v[172:173], v[198:199] op_sel_hi:[1,0]
	v_cndmask_b32_e64 v199, v196, 0, s[28:29]
	v_fma_f32 v196, v228, s42, -v199
	v_fma_f32 v216, v216, s42, -v199
	v_exp_f32_e32 v197, v197
	v_exp_f32_e32 v196, v196
	v_exp_f32_e32 v228, v216
	v_pk_mul_f32 v[122:123], v[122:123], v[214:215] op_sel_hi:[1,0]
	v_pk_mul_f32 v[120:121], v[120:121], v[214:215] op_sel_hi:[1,0]
	v_pk_mul_f32 v[118:119], v[118:119], v[214:215] op_sel_hi:[1,0]
	v_pk_mul_f32 v[116:117], v[116:117], v[214:215] op_sel_hi:[1,0]
; template <int NT, int NKK, int NDT, int MODE, bool MASK> ...
;     ...
;     for (int jh = 0; jh < NT / JB; ++jh) {
;       int oz = 0; if (NT > JB) asm volatile("" : "+v"(oz));
;       f32x4 s[JB][2];
;       __builtin_amdgcn_s_setprio(1);
; #pragma unroll
;       for (int t = 0; t < 2; ++t)
; #pragma unroll
;         for (int kk = 0; kk < NKK; ++kk) {
;           const bf16x8 kf = *(LAS const bf16x8*)(Kl + oz + (32 * st + 16 * t + r) * KSTR + (32 * kk + 8 * lg) * 2);
; #pragma unroll
;           for (int jj = 0; jj < JB; ++jj) s[jj][t] = mfma16(kf, qf[jh * JB + jj][kk], kk == 0 ? (f32x4){0.f, 0.f, 0.f, 0.f} : s[jj][t]);
;         }
;       __builtin_amdgcn_s_setprio(0);
;       bf16x8 pf[JB];
;       if (NT > JB) __builtin_amdgcn_sched_barrier(0);
; #pragma unroll
;       for (int jj = 0; jj < JB; ++jj) {
;         const int j = jh * JB + jj;
;         float mx = -INFINITY;
; #pragma unroll
;         for (int t = 0; t < 2; ++t)
; #pragma unroll
;           for (int i = 0; i < 4; ++i) {
;             if (MASK) { const int kp = kpos0 + 32 * st + 16 * t + 4 * lg + i; if (!mask_ok<MODE>(tq[j], kp, W)) s[jj][t][i] = -INFINITY; }
;             mx = fmaxf(mx, s[jj][t][i]);
;           }
;         mx = max_x16_x32(mx);
;         if (NT > 2 || __any(mx > m[j] + 8.0f / c)) {
;           const float mnew = fmaxf(m[j], mx);
;           const float ms2 = (mnew == -INFINITY) ? 0.f : mnew;
;           const float alpha = ex2((m[j] - ms2) * c);
;           m[j] = mnew; l[j] *= alpha;
; #pragma unroll
;           for (int dt = 0; dt < NDT; ++dt) o[j][dt] *= alpha;
;         }
;         const float mc = ((m[j] == -INFINITY) ? 0.f : m[j]) * c;
;         float p0[4], p1[4], ps = 0.f;
; #pragma unroll
;         for (int i = 0; i < 4; ++i) { p0[i] = ex2(s[jj][0][i] * c - mc); p1[i] = ex2(s[jj][1][i] * c - mc); ps += p0[i] + p1[i]; }
;         l[j] += ps;
;         pf[jj] = pack8(p0, p1);
;       }
;       if (NT > JB) __builtin_amdgcn_sched_barrier(0);
;       __builtin_amdgcn_s_setprio(1);
; #pragma unroll
;       for (int dt = 0; dt < NDT; ++dt) {
;         const s16x4 v0 = ds_tr(Vl + oz + (32 * st + 4 * lg + vq) * VSTR + (16 * dt + 4 * vp) * 2);
;         const s16x4 v1 = ds_tr(Vl + oz + (32 * st + 16 + 4 * lg + vq) * VSTR + (16 * dt + 4 * vp) * 2);
;         const bf16x8 vf = (bf16x8){v0[0], v0[1], v0[2], v0[3], v1[0], v1[1], v1[2], v1[3]};
; #pragma unroll
	v_pk_mul_f32 v[134:135], v[134:135], v[214:215] op_sel_hi:[1,0]
	v_pk_mul_f32 v[132:133], v[132:133], v[214:215] op_sel_hi:[1,0]
	v_pk_mul_f32 v[142:143], v[142:143], v[214:215] op_sel_hi:[1,0]
	v_fma_f32 v215, v215, s42, -v199
	v_cvt_pk_bf16_f32 v222, v197, v231
	v_exp_f32_e32 v230, v215
	v_fma_f32 v215, v217, s42, -v199
	v_pk_add_f32 v[216:217], v[196:197], v[228:229]
	v_fma_f32 v197, v238, s42, -v199
	v_exp_f32_e32 v238, v197
	v_fma_f32 v197, v220, s42, -v199
	v_exp_f32_e32 v236, v215
	v_exp_f32_e32 v240, v197
	v_fma_f32 v197, v242, s42, -v199
	v_exp_f32_e32 v242, v197
	v_fma_f32 v197, v221, s42, -v199
	v_exp_f32_e32 v244, v197
	v_pk_add_f32 v[218:219], v[230:231], v[236:237]
	v_pk_mul_f32 v[140:141], v[140:141], v[214:215] op_sel_hi:[1,0]
	v_mov_b32_e32 v215, v198
	v_pk_add_f32 v[198:199], v[218:219], v[216:217]
	v_pk_add_f32 v[216:217], v[238:239], v[240:241]
	v_cvt_pk_bf16_f32 v223, v239, v243
	v_pk_add_f32 v[198:199], v[216:217], v[198:199]
	v_pk_add_f32 v[216:217], v[242:243], v[244:245]
	v_cvt_pk_bf16_f32 v224, v229, v237
	v_pk_add_f32 v[198:199], v[216:217], v[198:199]
	v_cvt_pk_bf16_f32 v225, v241, v245
	v_pk_fma_f32 v[194:195], v[194:195], v[214:215], v[198:199]
	v_cvt_pk_bf16_f32 v214, v196, v230
	v_cvt_pk_bf16_f32 v215, v238, v242
	v_cvt_pk_bf16_f32 v216, v228, v236
	v_cvt_pk_bf16_f32 v217, v240, v244
	s_setprio 1
	v_add3_u32 v196, v213, v246, v206
	ds_read_b64_tr_b16 v[220:221], v196 offset:11776
	ds_read_b64_tr_b16 v[218:219], v196 offset:9216
	ds_read_b64_tr_b16 v[228:229], v196 offset:9248
	ds_read_b64_tr_b16 v[230:231], v196 offset:11808
	s_waitcnt lgkmcnt(2)
	v_mfma_f32_16x16x32_bf16 v[152:155], v[218:221], v[222:225], v[152:155]
	v_mfma_f32_16x16x32_bf16 v[120:123], v[218:221], v[214:217], v[120:123]
	ds_read_b64_tr_b16 v[218:219], v196 offset:9280
	ds_read_b64_tr_b16 v[220:221], v196 offset:11840
	s_waitcnt lgkmcnt(0)
	v_mfma_f32_16x16x32_bf16 v[164:167], v[218:221], v[222:225], v[164:167]
	v_mfma_f32_16x16x32_bf16 v[132:135], v[218:221], v[214:217], v[132:135]
	ds_read_b64_tr_b16 v[218:219], v196 offset:9312
	ds_read_b64_tr_b16 v[220:221], v196 offset:11872
	v_mfma_f32_16x16x32_bf16 v[148:151], v[228:231], v[222:225], v[148:151]
	v_mfma_f32_16x16x32_bf16 v[116:119], v[228:231], v[214:217], v[116:119]
	s_waitcnt lgkmcnt(0)
	v_mfma_f32_16x16x32_bf16 v[172:175], v[218:221], v[222:225], v[172:175]
	v_mfma_f32_16x16x32_bf16 v[140:143], v[218:221], v[214:217], v[140:143]
	s_setprio 0
	v_mov_b32_e32 v248, 0
	s_setprio 1
	v_add3_u32 v196, v207, v248, v247
	ds_read_b128 v[214:217], v196
	ds_read_b128 v[218:221], v196 offset:64
	ds_read_b128 v[228:231], v196 offset:2304
	ds_read_b128 v[236:239], v196 offset:2368
	s_waitcnt lgkmcnt(3)
	v_mfma_f32_16x16x32_bf16 v[222:225], v[214:217], v[28:31], 0
	v_mfma_f32_16x16x32_bf16 v[214:217], v[214:217], v[36:39], 0
	s_waitcnt lgkmcnt(1)
	v_mfma_f32_16x16x32_bf16 v[240:243], v[228:231], v[28:31], 0
	v_mfma_f32_16x16x32_bf16 v[228:231], v[228:231], v[36:39], 0
	v_mfma_f32_16x16x32_bf16 v[222:225], v[218:221], v[32:35], v[222:225]
	v_mfma_f32_16x16x32_bf16 v[216:219], v[218:221], v[40:43], v[214:217]
	s_waitcnt lgkmcnt(0)
; template <int NT, int NKK, int NDT, int MODE, bool MASK> ...
;     ...
;     for (int jh = 0; jh < NT / JB; ++jh) {
;       int oz = 0; if (NT > JB) asm volatile("" : "+v"(oz));
;       f32x4 s[JB][2];
;       __builtin_amdgcn_s_setprio(1);
; #pragma unroll
;       for (int t = 0; t < 2; ++t)
; #pragma unroll
;         for (int kk = 0; kk < NKK; ++kk) {
;           const bf16x8 kf = *(LAS const bf16x8*)(Kl + oz + (32 * st + 16 * t + r) * KSTR + (32 * kk + 8 * lg) * 2);
; #pragma unroll
;           for (int jj = 0; jj < JB; ++jj) s[jj][t] = mfma16(kf, qf[jh * JB + jj][kk], kk == 0 ? (f32x4){0.f, 0.f, 0.f, 0.f} : s[jj][t]);
;         }
;       __builtin_amdgcn_s_setprio(0);
;       bf16x8 pf[JB];
;       if (NT > JB) __builtin_amdgcn_sched_barrier(0);
; #pragma unroll
;       for (int jj = 0; jj < JB; ++jj) {
;         const int j = jh * JB + jj;
;         float mx = -INFINITY;
; #pragma unroll
;         for (int t = 0; t < 2; ++t)
; #pragma unroll
;           for (int i = 0; i < 4; ++i) {
;             if (MASK) { const int kp = kpos0 + 32 * st + 16 * t + 4 * lg + i; if (!mask_ok<MODE>(tq[j], kp, W)) s[jj][t][i] = -INFINITY; }
;             mx = fmaxf(mx, s[jj][t][i]);
;           }
;         mx = max_x16_x32(mx);
;         if (NT > 2 || __any(mx > m[j] + 8.0f / c)) {
;           const float mnew = fmaxf(m[j], mx);
;           const float ms2 = (mnew == -INFINITY) ? 0.f : mnew;
;           const float alpha = ex2((m[j] - ms2) * c);
;           m[j] = mnew; l[j] *= alpha;
; #pragma unroll
;           for (int dt = 0; dt < NDT; ++dt) o[j][dt] *= alpha;
;         }
;         const float mc = ((m[j] == -INFINITY) ? 0.f : m[j]) * c;
;         float p0[4], p1[4], ps = 0.f;
; #pragma unroll
;         for (int i = 0; i < 4; ++i) { p0[i] = ex2(s[jj][0][i] * c - mc); p1[i] = ex2(s[jj][1][i] * c - mc); ps += p0[i] + p1[i]; }
;         l[j] += ps;
;         pf[jj] = pack8(p0, p1);
;       }
;       if (NT > JB) __builtin_amdgcn_sched_barrier(0);
;       __builtin_amdgcn_s_setprio(1);
; #pragma unroll
;       for (int dt = 0; dt < NDT; ++dt) {
;         const s16x4 v0 = ds_tr(Vl + oz + (32 * st + 4 * lg + vq) * VSTR + (16 * dt + 4 * vp) * 2);
;         const s16x4 v1 = ds_tr(Vl + oz + (32 * st + 16 + 4 * lg + vq) * VSTR + (16 * dt + 4 * vp) * 2);
;         const bf16x8 vf = (bf16x8){v0[0], v0[1], v0[2], v0[3], v1[0], v1[1], v1[2], v1[3]};
; #pragma unroll
	v_mfma_f32_16x16x32_bf16 v[240:243], v[236:239], v[32:35], v[240:243]
	v_mfma_f32_16x16x32_bf16 v[228:231], v[236:239], v[40:43], v[228:231]
	s_setprio 0
	v_mov_b32_e32 v196, s81
	s_nop 0
	s_nop 0
	v_cndmask_b32_e32 v197, v196, v222, vcc
	v_cndmask_b32_e64 v199, v200, v223, s[12:13]
	v_max3_f32 v196, v197, s81, v199
	v_cndmask_b32_e64 v215, v200, v224, s[14:15]
	v_cndmask_b32_e64 v220, v200, v225, s[16:17]
	v_max3_f32 v198, v196, v215, v220
	v_mov_b32_e32 v196, s81
	v_cndmask_b32_e64 v196, v196, v240, s[18:19]
	v_cndmask_b32_e64 v221, v200, v241, s[20:21]
	v_max3_f32 v198, v198, v196, v221
	v_cndmask_b32_e64 v222, v200, v242, s[22:23]
	v_cndmask_b32_e64 v223, v200, v243, s[24:25]
	v_max3_f32 v198, v198, v222, v223
	v_mov_b32_e32 v214, v198
	s_nop 1
	v_permlane16_swap_b32_e32 v198, v214
	v_max_f32_e32 v198, v198, v214
	v_mov_b32_e32 v214, v198
	s_nop 1
	v_permlane32_swap_b32_e32 v198, v214
	v_max3_f32 v214, v232, v198, v214
	v_cmp_eq_f32_e64 s[28:29], s81, v214
	v_mul_f32_e32 v224, 0x3e38aa3b, v214
	v_cndmask_b32_e64 v217, v200, v217, s[12:13]
	v_cndmask_b32_e64 v224, v224, 0, s[28:29]
	v_fma_f32 v196, v196, s42, -v224
	v_cndmask_b32_e64 v198, v214, 0, s[28:29]
	v_exp_f32_e32 v225, v196
	v_fma_f32 v196, v199, s42, -v224
	v_sub_f32_e32 v198, v232, v198
	v_exp_f32_e32 v237, v196
	v_fma_f32 v196, v221, s42, -v224
	v_mul_f32_e32 v198, 0x3e38aa3b, v198
	v_exp_f32_e32 v239, v196
	v_fma_f32 v196, v215, s42, -v224
	v_exp_f32_e32 v198, v198
	v_exp_f32_e32 v241, v196
	v_fma_f32 v196, v222, s42, -v224
	v_exp_f32_e32 v243, v196
	v_fma_f32 v196, v220, s42, -v224
	v_exp_f32_e32 v245, v196
	v_fma_f32 v196, v223, s42, -v224
	v_exp_f32_e32 v247, v196
	v_mov_b32_e32 v196, s81
	v_pk_mul_f32 v[162:163], v[162:163], v[198:199] op_sel_hi:[1,0]
	v_pk_mul_f32 v[160:161], v[160:161], v[198:199] op_sel_hi:[1,0]
	v_pk_mul_f32 v[158:159], v[158:159], v[198:199] op_sel_hi:[1,0]
	v_pk_mul_f32 v[156:157], v[156:157], v[198:199] op_sel_hi:[1,0]
	v_pk_mul_f32 v[170:171], v[170:171], v[198:199] op_sel_hi:[1,0]
	v_pk_mul_f32 v[168:169], v[168:169], v[198:199] op_sel_hi:[1,0]
	v_pk_mul_f32 v[178:179], v[178:179], v[198:199] op_sel_hi:[1,0]
	v_pk_mul_f32 v[176:177], v[176:177], v[198:199] op_sel_hi:[1,0]
	v_cndmask_b32_e32 v199, v196, v216, vcc
	v_max3_f32 v196, v199, s81, v217
	v_cndmask_b32_e64 v232, v200, v218, s[14:15]
	v_cndmask_b32_e64 v244, v200, v219, s[16:17]
	v_max3_f32 v215, v196, v232, v244
	v_mov_b32_e32 v196, s81
	v_cndmask_b32_e64 v218, v196, v228, s[18:19]
	v_cndmask_b32_e64 v219, v200, v229, s[20:21]
	v_max3_f32 v196, v215, v218, v219
	v_cndmask_b32_e64 v230, v200, v230, s[22:23]
	v_cndmask_b32_e64 v231, v200, v231, s[24:25]
	v_max3_f32 v196, v196, v230, v231
	v_mov_b32_e32 v215, v196
	s_nop 1
	v_permlane16_swap_b32_e32 v196, v215
	v_max_f32_e32 v196, v196, v215
	v_mov_b32_e32 v215, v196
	s_nop 1
	v_permlane32_swap_b32_e32 v196, v215
	v_max3_f32 v215, v235, v196, v215
	v_cmp_eq_f32_e32 vcc, s81, v215
	v_fma_f32 v197, v197, s42, -v224
	v_exp_f32_e32 v197, v197
	v_cndmask_b32_e64 v196, v215, 0, vcc
	v_sub_f32_e32 v196, v235, v196
	v_mul_f32_e32 v196, 0x3e38aa3b, v196
	v_exp_f32_e32 v216, v196
	v_mul_f32_e32 v196, 0x3e38aa3b, v215
	v_cndmask_b32_e64 v235, v196, 0, vcc
	v_fma_f32 v196, v199, s42, -v235
	v_fma_f32 v199, v218, s42, -v235
	v_exp_f32_e32 v196, v196
	v_exp_f32_e32 v224, v199
	v_fma_f32 v199, v217, s42, -v235
	v_cvt_pk_bf16_f32 v220, v197, v237
	v_exp_f32_e32 v236, v199
	v_fma_f32 v199, v219, s42, -v235
	v_pk_add_f32 v[218:219], v[196:197], v[224:225]
	v_fma_f32 v197, v232, s42, -v235
	v_exp_f32_e32 v240, v197
	v_fma_f32 v197, v230, s42, -v235
	v_exp_f32_e32 v238, v199
	v_exp_f32_e32 v242, v197
	v_fma_f32 v197, v244, s42, -v235
	v_exp_f32_e32 v244, v197
	v_fma_f32 v197, v231, s42, -v235
	v_exp_f32_e32 v246, v197
	v_pk_add_f32 v[228:229], v[236:237], v[238:239]
	v_pk_mul_f32 v[130:131], v[130:131], v[216:217] op_sel_hi:[1,0]
	v_pk_mul_f32 v[128:129], v[128:129], v[216:217] op_sel_hi:[1,0]
	v_pk_mul_f32 v[126:127], v[126:127], v[216:217] op_sel_hi:[1,0]
	v_pk_mul_f32 v[124:125], v[124:125], v[216:217] op_sel_hi:[1,0]
	v_pk_mul_f32 v[138:139], v[138:139], v[216:217] op_sel_hi:[1,0]
	v_pk_mul_f32 v[136:137], v[136:137], v[216:217] op_sel_hi:[1,0]
	v_pk_mul_f32 v[146:147], v[146:147], v[216:217] op_sel_hi:[1,0]
	v_pk_mul_f32 v[144:145], v[144:145], v[216:217] op_sel_hi:[1,0]
	v_mov_b32_e32 v217, v198
	v_pk_add_f32 v[198:199], v[228:229], v[218:219]
	v_pk_add_f32 v[218:219], v[240:241], v[242:243]
	v_cvt_pk_bf16_f32 v221, v241, v245
	v_pk_add_f32 v[198:199], v[218:219], v[198:199]
	v_pk_add_f32 v[218:219], v[244:245], v[246:247]
	v_cvt_pk_bf16_f32 v222, v225, v239
	v_pk_add_f32 v[198:199], v[218:219], v[198:199]
	v_cvt_pk_bf16_f32 v223, v243, v247
	v_pk_fma_f32 v[202:203], v[202:203], v[216:217], v[198:199]
	v_cvt_pk_bf16_f32 v216, v196, v236
	v_cvt_pk_bf16_f32 v217, v240, v244
	v_cvt_pk_bf16_f32 v218, v224, v238
	v_cvt_pk_bf16_f32 v219, v242, v246
	s_setprio 1
	v_add3_u32 v196, v213, v248, v206
	ds_read_b64_tr_b16 v[230:231], v196 offset:11776
	ds_read_b64_tr_b16 v[228:229], v196 offset:9216
	ds_read_b64_tr_b16 v[236:237], v196 offset:9248
	ds_read_b64_tr_b16 v[238:239], v196 offset:11808
	s_waitcnt lgkmcnt(2)
	v_mfma_f32_16x16x32_bf16 v[160:163], v[228:231], v[220:223], v[160:163]
	v_mfma_f32_16x16x32_bf16 v[128:131], v[228:231], v[216:219], v[128:131]
	ds_read_b64_tr_b16 v[228:229], v196 offset:9280
	ds_read_b64_tr_b16 v[230:231], v196 offset:11840
	s_waitcnt lgkmcnt(0)
	v_mfma_f32_16x16x32_bf16 v[168:171], v[228:231], v[220:223], v[168:171]
	v_mfma_f32_16x16x32_bf16 v[136:139], v[228:231], v[216:219], v[136:139]
	ds_read_b64_tr_b16 v[228:229], v196 offset:9312
	ds_read_b64_tr_b16 v[230:231], v196 offset:11872
	v_mfma_f32_16x16x32_bf16 v[156:159], v[236:239], v[220:223], v[156:159]
	v_mfma_f32_16x16x32_bf16 v[124:127], v[236:239], v[216:219], v[124:127]
	s_waitcnt lgkmcnt(0)
	v_mfma_f32_16x16x32_bf16 v[176:179], v[228:231], v[220:223], v[176:179]
	v_mfma_f32_16x16x32_bf16 v[144:147], v[228:231], v[216:219], v[144:147]
	s_setprio 0
	s_mov_b32 s8, 32
	s_and_b64 vcc, exec, s[70:71]
	s_mov_b64 s[70:71], 0
	s_cbranch_vccnz .LBB0_1265
	s_mov_b64 s[12:13], 0

; template <int NT, int NKK, int NDT, int MODE, bool MASK> ...
;     ...
;     for (int jh = 0; jh < NT / JB; ++jh) {
;       int oz = 0; if (NT > JB) asm volatile("" : "+v"(oz));
;       f32x4 s[JB][2];
;       __builtin_amdgcn_s_setprio(1);
; #pragma unroll
;       for (int t = 0; t < 2; ++t)
; #pragma unroll
;         for (int kk = 0; kk < NKK; ++kk) {
;           const bf16x8 kf = *(LAS const bf16x8*)(Kl + oz + (32 * st + 16 * t + r) * KSTR + (32 * kk + 8 * lg) * 2);
; #pragma unroll
;           for (int jj = 0; jj < JB; ++jj) s[jj][t] = mfma16(kf, qf[jh * JB + jj][kk], kk == 0 ? (f32x4){0.f, 0.f, 0.f, 0.f} : s[jj][t]);
;         }
;       __builtin_amdgcn_s_setprio(0);
;       bf16x8 pf[JB];
;       if (NT > JB) __builtin_amdgcn_sched_barrier(0);
; #pragma unroll
;       for (int jj = 0; jj < JB; ++jj) {
;         const int j = jh * JB + jj;
;         float mx = -INFINITY;
; #pragma unroll
;         for (int t = 0; t < 2; ++t)
; #pragma unroll
;           for (int i = 0; i < 4; ++i) {
;             if (MASK) { const int kp = kpos0 + 32 * st + 16 * t + 4 * lg + i; if (!mask_ok<MODE>(tq[j], kp, W)) s[jj][t][i] = -INFINITY; }
;             mx = fmaxf(mx, s[jj][t][i]);
;           }
;         mx = max_x16_x32(mx);
;         if (NT > 2 || __any(mx > m[j] + 8.0f / c)) {
;           const float mnew = fmaxf(m[j], mx);
;           const float ms2 = (mnew == -INFINITY) ? 0.f : mnew;
;           const float alpha = ex2((m[j] - ms2) * c);
;           m[j] = mnew; l[j] *= alpha;
; #pragma unroll
;           for (int dt = 0; dt < NDT; ++dt) o[j][dt] *= alpha;
;         }
;         const float mc = ((m[j] == -INFINITY) ? 0.f : m[j]) * c;
;         float p0[4], p1[4], ps = 0.f;
; #pragma unroll
;         for (int i = 0; i < 4; ++i) { p0[i] = ex2(s[jj][0][i] * c - mc); p1[i] = ex2(s[jj][1][i] * c - mc); ps += p0[i] + p1[i]; }
;         l[j] += ps;
;         pf[jj] = pack8(p0, p1);
;       }
;       if (NT > JB) __builtin_amdgcn_sched_barrier(0);
;       __builtin_amdgcn_s_setprio(1);
; #pragma unroll
;       for (int dt = 0; dt < NDT; ++dt) {
;         const s16x4 v0 = ds_tr(Vl + oz + (32 * st + 4 * lg + vq) * VSTR + (16 * dt + 4 * vp) * 2);
;         const s16x4 v1 = ds_tr(Vl + oz + (32 * st + 16 + 4 * lg + vq) * VSTR + (16 * dt + 4 * vp) * 2);
;         const bf16x8 vf = (bf16x8){v0[0], v0[1], v0[2], v0[3], v1[0], v1[1], v1[2], v1[3]};
; #pragma unroll
.LBB0_1281:
	v_mov_b32_e32 v197, v1
	v_or_b32_e32 v1, s8, v211
	v_cmp_le_i32_e32 vcc, v1, v182
	v_cmp_gt_i32_e64 s[12:13], v1, v208
	s_and_b64 vcc, vcc, s[12:13]
	v_cmp_lt_i32_e64 s[12:13], v1, v182
	v_cmp_ge_i32_e64 s[14:15], v1, v208
	v_or_b32_e32 v196, 2, v1
	s_and_b64 s[12:13], s[12:13], s[14:15]
	v_cmp_le_i32_e64 s[14:15], v196, v182
	v_cmp_gt_i32_e64 s[16:17], v196, v208
	v_or_b32_e32 v196, 3, v1
	s_and_b64 s[14:15], s[14:15], s[16:17]
	v_cmp_le_i32_e64 s[16:17], v196, v182
	v_cmp_gt_i32_e64 s[18:19], v196, v208
	v_or_b32_e32 v196, 16, v1
	s_and_b64 s[16:17], s[16:17], s[18:19]
	v_cmp_le_i32_e64 s[18:19], v196, v182
	v_cmp_gt_i32_e64 s[20:21], v196, v208
	v_or_b32_e32 v196, 17, v1
	s_and_b64 s[18:19], s[18:19], s[20:21]
	v_cmp_le_i32_e64 s[20:21], v196, v182
	v_cmp_gt_i32_e64 s[22:23], v196, v208
	v_or_b32_e32 v196, 18, v1
	s_and_b64 s[20:21], s[20:21], s[22:23]
	v_cmp_le_i32_e64 s[22:23], v196, v182
	v_cmp_gt_i32_e64 s[24:25], v196, v208
	v_or_b32_e32 v1, 19, v1
	s_and_b64 s[22:23], s[22:23], s[24:25]
	v_cmp_le_i32_e64 s[24:25], v1, v182
	v_cmp_gt_i32_e64 s[28:29], v1, v208
	v_or_b32_e32 v1, s8, v183
	v_or_b32_e32 v196, s8, v204
	v_mov_b32_e32 v246, 0
	v_mov_b32_e32 v199, v212
	v_mov_b32_e32 v232, v214
	v_mov_b32_e32 v235, v215
	s_and_b64 s[24:25], s[24:25], s[28:29]
	v_mad_u32_u24 v213, v196, s80, 0
	s_setprio 1
	v_mul_u32_u24_e32 v247, 0x90, v1
	v_add3_u32 v1, v207, v246, v247
	ds_read_b128 v[214:217], v1 offset:19456
	ds_read_b128 v[218:221], v1 offset:19520
	s_waitcnt lgkmcnt(1)
	v_mfma_f32_16x16x32_bf16 v[222:225], v[214:217], v[12:15], 0
	v_mfma_f32_16x16x32_bf16 v[214:217], v[214:217], v[20:23], 0
	s_waitcnt lgkmcnt(0)
	v_mfma_f32_16x16x32_bf16 v[222:225], v[218:221], v[16:19], v[222:225]
	v_mfma_f32_16x16x32_bf16 v[214:217], v[218:221], v[24:27], v[214:217]
	ds_read_b128 v[218:221], v1 offset:21760
	ds_read_b128 v[228:231], v1 offset:21824
	s_waitcnt lgkmcnt(1)
	v_mfma_f32_16x16x32_bf16 v[236:239], v[218:221], v[12:15], 0
	v_mfma_f32_16x16x32_bf16 v[218:221], v[218:221], v[20:23], 0
	s_waitcnt lgkmcnt(0)
	v_mfma_f32_16x16x32_bf16 v[236:239], v[228:231], v[16:19], v[236:239]
	v_mfma_f32_16x16x32_bf16 v[218:221], v[228:231], v[24:27], v[218:221]
	s_setprio 0
	v_mov_b32_e32 v196, s81
	v_cndmask_b32_e32 v212, v196, v222, vcc
	v_cndmask_b32_e64 v222, v200, v223, s[12:13]
	v_max3_f32 v1, v212, s81, v222
	v_cndmask_b32_e64 v223, v200, v224, s[14:15]
	v_cndmask_b32_e64 v224, v200, v225, s[16:17]
	v_max3_f32 v1, v1, v223, v224
	v_cndmask_b32_e64 v196, v196, v236, s[18:19]
	v_cndmask_b32_e64 v225, v200, v237, s[20:21]
	v_max3_f32 v1, v1, v196, v225
	v_cndmask_b32_e64 v228, v200, v238, s[22:23]
	v_cndmask_b32_e64 v230, v200, v239, s[24:25]
	v_max3_f32 v1, v1, v228, v230
	v_mov_b32_e32 v198, v1
	s_nop 1
	v_permlane16_swap_b32_e32 v1, v198
	v_max_f32_e32 v1, v1, v198
	v_mov_b32_e32 v198, v1
	s_nop 1
	v_permlane32_swap_b32_e32 v1, v198
	v_max3_f32 v1, v197, v1, v198
	v_cmp_eq_f32_e64 s[28:29], s81, v1
	v_cndmask_b32_e64 v215, v200, v215, s[12:13]
	v_cndmask_b32_e64 v216, v200, v216, s[14:15]
	v_cndmask_b32_e64 v198, v1, 0, s[28:29]
	v_sub_f32_e32 v197, v197, v198
	v_mul_f32_e32 v197, 0x3e38aa3b, v197
	v_exp_f32_e32 v198, v197
	v_mul_f32_e32 v197, 0x3e38aa3b, v1
	v_cndmask_b32_e64 v236, v197, 0, s[28:29]
	v_fma_f32 v196, v196, s42, -v236
	v_exp_f32_e32 v229, v196
	v_fma_f32 v196, v222, s42, -v236
	v_exp_f32_e32 v231, v196
	v_fma_f32 v196, v225, s42, -v236
	v_exp_f32_e32 v237, v196
	v_fma_f32 v196, v223, s42, -v236
	v_exp_f32_e32 v239, v196
	v_fma_f32 v196, v228, s42, -v236
	v_exp_f32_e32 v241, v196
	v_fma_f32 v196, v224, s42, -v236
	v_exp_f32_e32 v243, v196
	v_fma_f32 v196, v230, s42, -v236
	v_exp_f32_e32 v245, v196
	v_mov_b32_e32 v196, s81
	v_cndmask_b32_e32 v228, v196, v214, vcc
	v_max3_f32 v196, v228, s81, v215
	v_cndmask_b32_e64 v217, v200, v217, s[16:17]
	v_fma_f32 v197, v212, s42, -v236
	v_max3_f32 v212, v196, v216, v217
	v_mov_b32_e32 v196, s81
	v_cndmask_b32_e64 v218, v196, v218, s[18:19]
	v_cndmask_b32_e64 v219, v200, v219, s[20:21]
	v_max3_f32 v196, v212, v218, v219
	v_cndmask_b32_e64 v220, v200, v220, s[22:23]
	v_cndmask_b32_e64 v221, v200, v221, s[24:25]
	v_max3_f32 v196, v196, v220, v221
	v_mov_b32_e32 v212, v196
	s_nop 1
	v_permlane16_swap_b32_e32 v196, v212
	v_max_f32_e32 v196, v196, v212
	v_mov_b32_e32 v212, v196
	s_nop 1
	v_permlane32_swap_b32_e32 v196, v212
	v_max3_f32 v212, v199, v196, v212
	v_cmp_eq_f32_e64 s[28:29], s81, v212
	v_pk_mul_f32 v[154:155], v[154:155], v[198:199] op_sel_hi:[1,0]
	v_pk_mul_f32 v[152:153], v[152:153], v[198:199] op_sel_hi:[1,0]
	v_cndmask_b32_e64 v196, v212, 0, s[28:29]
	v_sub_f32_e32 v196, v199, v196
	v_mul_f32_e32 v196, 0x3e38aa3b, v196
	v_exp_f32_e32 v214, v196
	v_mul_f32_e32 v196, 0x3e38aa3b, v212
	v_pk_mul_f32 v[150:151], v[150:151], v[198:199] op_sel_hi:[1,0]
	v_pk_mul_f32 v[148:149], v[148:149], v[198:199] op_sel_hi:[1,0]
	v_pk_mul_f32 v[166:167], v[166:167], v[198:199] op_sel_hi:[1,0]
	v_pk_mul_f32 v[164:165], v[164:165], v[198:199] op_sel_hi:[1,0]
	v_pk_mul_f32 v[174:175], v[174:175], v[198:199] op_sel_hi:[1,0]
	v_pk_mul_f32 v[172:173], v[172:173], v[198:199] op_sel_hi:[1,0]
	v_cndmask_b32_e64 v199, v196, 0, s[28:29]
	v_pk_mul_f32 v[122:123], v[122:123], v[214:215] op_sel_hi:[1,0]
	v_pk_mul_f32 v[120:121], v[120:121], v[214:215] op_sel_hi:[1,0]
	v_pk_mul_f32 v[118:119], v[118:119], v[214:215] op_sel_hi:[1,0]
	v_pk_mul_f32 v[116:117], v[116:117], v[214:215] op_sel_hi:[1,0]
	v_pk_mul_f32 v[134:135], v[134:135], v[214:215] op_sel_hi:[1,0]
	v_pk_mul_f32 v[132:133], v[132:133], v[214:215] op_sel_hi:[1,0]
	v_pk_mul_f32 v[142:143], v[142:143], v[214:215] op_sel_hi:[1,0]
; template <int NT, int NKK, int NDT, int MODE, bool MASK> ...
;     ...
;     for (int jh = 0; jh < NT / JB; ++jh) {
;       int oz = 0; if (NT > JB) asm volatile("" : "+v"(oz));
;       f32x4 s[JB][2];
;       __builtin_amdgcn_s_setprio(1);
; #pragma unroll
;       for (int t = 0; t < 2; ++t)
; #pragma unroll
;         for (int kk = 0; kk < NKK; ++kk) {
;           const bf16x8 kf = *(LAS const bf16x8*)(Kl + oz + (32 * st + 16 * t + r) * KSTR + (32 * kk + 8 * lg) * 2);
; #pragma unroll
;           for (int jj = 0; jj < JB; ++jj) s[jj][t] = mfma16(kf, qf[jh * JB + jj][kk], kk == 0 ? (f32x4){0.f, 0.f, 0.f, 0.f} : s[jj][t]);
;         }
;       __builtin_amdgcn_s_setprio(0);
;       bf16x8 pf[JB];
;       if (NT > JB) __builtin_amdgcn_sched_barrier(0);
; #pragma unroll
;       for (int jj = 0; jj < JB; ++jj) {
;         const int j = jh * JB + jj;
;         float mx = -INFINITY;
; #pragma unroll
;         for (int t = 0; t < 2; ++t)
; #pragma unroll
;           for (int i = 0; i < 4; ++i) {
;             if (MASK) { const int kp = kpos0 + 32 * st + 16 * t + 4 * lg + i; if (!mask_ok<MODE>(tq[j], kp, W)) s[jj][t][i] = -INFINITY; }
;             mx = fmaxf(mx, s[jj][t][i]);
;           }
;         mx = max_x16_x32(mx);
;         if (NT > 2 || __any(mx > m[j] + 8.0f / c)) {
;           const float mnew = fmaxf(m[j], mx);
;           const float ms2 = (mnew == -INFINITY) ? 0.f : mnew;
;           const float alpha = ex2((m[j] - ms2) * c);
;           m[j] = mnew; l[j] *= alpha;
; #pragma unroll
;           for (int dt = 0; dt < NDT; ++dt) o[j][dt] *= alpha;
;         }
;         const float mc = ((m[j] == -INFINITY) ? 0.f : m[j]) * c;
;         float p0[4], p1[4], ps = 0.f;
; #pragma unroll
;         for (int i = 0; i < 4; ++i) { p0[i] = ex2(s[jj][0][i] * c - mc); p1[i] = ex2(s[jj][1][i] * c - mc); ps += p0[i] + p1[i]; }
;         l[j] += ps;
;         pf[jj] = pack8(p0, p1);
;       }
;       if (NT > JB) __builtin_amdgcn_sched_barrier(0);
;       __builtin_amdgcn_s_setprio(1);
; #pragma unroll
;       for (int dt = 0; dt < NDT; ++dt) {
;         const s16x4 v0 = ds_tr(Vl + oz + (32 * st + 4 * lg + vq) * VSTR + (16 * dt + 4 * vp) * 2);
;         const s16x4 v1 = ds_tr(Vl + oz + (32 * st + 16 + 4 * lg + vq) * VSTR + (16 * dt + 4 * vp) * 2);
;         const bf16x8 vf = (bf16x8){v0[0], v0[1], v0[2], v0[3], v1[0], v1[1], v1[2], v1[3]};
; #pragma unroll
	v_pk_mul_f32 v[140:141], v[140:141], v[214:215] op_sel_hi:[1,0]
	v_fma_f32 v215, v215, s42, -v199
	v_fma_f32 v196, v228, s42, -v199
	v_fma_f32 v218, v218, s42, -v199
	v_exp_f32_e32 v230, v215
	v_fma_f32 v215, v219, s42, -v199
	v_exp_f32_e32 v197, v197
	v_exp_f32_e32 v196, v196
	v_exp_f32_e32 v228, v218
	v_exp_f32_e32 v236, v215
	v_fma_f32 v215, v216, s42, -v199
	v_exp_f32_e32 v238, v215
	v_fma_f32 v215, v220, s42, -v199
	v_exp_f32_e32 v240, v215
	v_fma_f32 v215, v217, s42, -v199
	v_fma_f32 v199, v221, s42, -v199
	v_exp_f32_e32 v242, v215
	v_exp_f32_e32 v244, v199
	v_mov_b32_e32 v215, v198
	v_pk_add_f32 v[198:199], v[196:197], v[228:229]
	v_pk_add_f32 v[216:217], v[230:231], v[236:237]
	v_cvt_pk_bf16_f32 v222, v197, v231
	v_pk_add_f32 v[198:199], v[216:217], v[198:199]
	v_pk_add_f32 v[216:217], v[238:239], v[240:241]
	v_cvt_pk_bf16_f32 v223, v239, v243
	v_pk_add_f32 v[198:199], v[216:217], v[198:199]
	v_pk_add_f32 v[216:217], v[242:243], v[244:245]
	v_cvt_pk_bf16_f32 v224, v229, v237
	v_pk_add_f32 v[198:199], v[216:217], v[198:199]
	v_cvt_pk_bf16_f32 v225, v241, v245
	v_pk_fma_f32 v[194:195], v[194:195], v[214:215], v[198:199]
	v_cvt_pk_bf16_f32 v214, v196, v230
	v_cvt_pk_bf16_f32 v215, v238, v242
	v_cvt_pk_bf16_f32 v216, v228, v236
	v_cvt_pk_bf16_f32 v217, v240, v244
	s_setprio 1
	v_add3_u32 v196, v213, v246, v206
	ds_read_b64_tr_b16 v[220:221], v196 offset:31232
	ds_read_b64_tr_b16 v[218:219], v196 offset:28672
	ds_read_b64_tr_b16 v[228:229], v196 offset:28704
	ds_read_b64_tr_b16 v[230:231], v196 offset:31264
	s_waitcnt lgkmcnt(2)
	v_mfma_f32_16x16x32_bf16 v[152:155], v[218:221], v[222:225], v[152:155]
	v_mfma_f32_16x16x32_bf16 v[120:123], v[218:221], v[214:217], v[120:123]
	ds_read_b64_tr_b16 v[218:219], v196 offset:28736
	ds_read_b64_tr_b16 v[220:221], v196 offset:31296
	s_waitcnt lgkmcnt(0)
	v_mfma_f32_16x16x32_bf16 v[164:167], v[218:221], v[222:225], v[164:167]
	v_mfma_f32_16x16x32_bf16 v[132:135], v[218:221], v[214:217], v[132:135]
	ds_read_b64_tr_b16 v[218:219], v196 offset:28768
	ds_read_b64_tr_b16 v[220:221], v196 offset:31328
	v_mfma_f32_16x16x32_bf16 v[148:151], v[228:231], v[222:225], v[148:151]
	v_mfma_f32_16x16x32_bf16 v[116:119], v[228:231], v[214:217], v[116:119]
	s_waitcnt lgkmcnt(0)
	v_mfma_f32_16x16x32_bf16 v[172:175], v[218:221], v[222:225], v[172:175]
	v_mfma_f32_16x16x32_bf16 v[140:143], v[218:221], v[214:217], v[140:143]
	s_setprio 0
	v_mov_b32_e32 v248, 0
	s_setprio 1
	v_add3_u32 v196, v207, v248, v247
	ds_read_b128 v[214:217], v196 offset:19456
	ds_read_b128 v[218:221], v196 offset:19520
	ds_read_b128 v[228:231], v196 offset:21760
	ds_read_b128 v[236:239], v196 offset:21824
	s_waitcnt lgkmcnt(3)
	v_mfma_f32_16x16x32_bf16 v[222:225], v[214:217], v[28:31], 0
	v_mfma_f32_16x16x32_bf16 v[214:217], v[214:217], v[36:39], 0
	s_waitcnt lgkmcnt(1)
	v_mfma_f32_16x16x32_bf16 v[240:243], v[228:231], v[28:31], 0
	v_mfma_f32_16x16x32_bf16 v[228:231], v[228:231], v[36:39], 0
	v_mfma_f32_16x16x32_bf16 v[222:225], v[218:221], v[32:35], v[222:225]
	v_mfma_f32_16x16x32_bf16 v[216:219], v[218:221], v[40:43], v[214:217]
	s_waitcnt lgkmcnt(0)
; template <int NT, int NKK, int NDT, int MODE, bool MASK> ...
;     ...
;     for (int jh = 0; jh < NT / JB; ++jh) {
;       int oz = 0; if (NT > JB) asm volatile("" : "+v"(oz));
;       f32x4 s[JB][2];
;       __builtin_amdgcn_s_setprio(1);
; #pragma unroll
;       for (int t = 0; t < 2; ++t)
; #pragma unroll
;         for (int kk = 0; kk < NKK; ++kk) {
;           const bf16x8 kf = *(LAS const bf16x8*)(Kl + oz + (32 * st + 16 * t + r) * KSTR + (32 * kk + 8 * lg) * 2);
; #pragma unroll
;           for (int jj = 0; jj < JB; ++jj) s[jj][t] = mfma16(kf, qf[jh * JB + jj][kk], kk == 0 ? (f32x4){0.f, 0.f, 0.f, 0.f} : s[jj][t]);
;         }
;       __builtin_amdgcn_s_setprio(0);
;       bf16x8 pf[JB];
;       if (NT > JB) __builtin_amdgcn_sched_barrier(0);
; #pragma unroll
;       for (int jj = 0; jj < JB; ++jj) {
;         const int j = jh * JB + jj;
;         float mx = -INFINITY;
; #pragma unroll
;         for (int t = 0; t < 2; ++t)
; #pragma unroll
;           for (int i = 0; i < 4; ++i) {
;             if (MASK) { const int kp = kpos0 + 32 * st + 16 * t + 4 * lg + i; if (!mask_ok<MODE>(tq[j], kp, W)) s[jj][t][i] = -INFINITY; }
;             mx = fmaxf(mx, s[jj][t][i]);
;           }
;         mx = max_x16_x32(mx);
;         if (NT > 2 || __any(mx > m[j] + 8.0f / c)) {
;           const float mnew = fmaxf(m[j], mx);
;           const float ms2 = (mnew == -INFINITY) ? 0.f : mnew;
;           const float alpha = ex2((m[j] - ms2) * c);
;           m[j] = mnew; l[j] *= alpha;
; #pragma unroll
;           for (int dt = 0; dt < NDT; ++dt) o[j][dt] *= alpha;
;         }
;         const float mc = ((m[j] == -INFINITY) ? 0.f : m[j]) * c;
;         float p0[4], p1[4], ps = 0.f;
; #pragma unroll
;         for (int i = 0; i < 4; ++i) { p0[i] = ex2(s[jj][0][i] * c - mc); p1[i] = ex2(s[jj][1][i] * c - mc); ps += p0[i] + p1[i]; }
;         l[j] += ps;
;         pf[jj] = pack8(p0, p1);
;       }
;       if (NT > JB) __builtin_amdgcn_sched_barrier(0);
;       __builtin_amdgcn_s_setprio(1);
; #pragma unroll
;       for (int dt = 0; dt < NDT; ++dt) {
;         const s16x4 v0 = ds_tr(Vl + oz + (32 * st + 4 * lg + vq) * VSTR + (16 * dt + 4 * vp) * 2);
;         const s16x4 v1 = ds_tr(Vl + oz + (32 * st + 16 + 4 * lg + vq) * VSTR + (16 * dt + 4 * vp) * 2);
;         const bf16x8 vf = (bf16x8){v0[0], v0[1], v0[2], v0[3], v1[0], v1[1], v1[2], v1[3]};
; #pragma unroll
	v_mfma_f32_16x16x32_bf16 v[240:243], v[236:239], v[32:35], v[240:243]
	v_mfma_f32_16x16x32_bf16 v[228:231], v[236:239], v[40:43], v[228:231]
	s_setprio 0
	v_mov_b32_e32 v196, s81
	s_nop 0
	s_nop 0
	v_cndmask_b32_e32 v197, v196, v222, vcc
	v_cndmask_b32_e64 v199, v200, v223, s[12:13]
	v_max3_f32 v196, v197, s81, v199
	v_cndmask_b32_e64 v215, v200, v224, s[14:15]
	v_cndmask_b32_e64 v220, v200, v225, s[16:17]
	v_max3_f32 v198, v196, v215, v220
	v_mov_b32_e32 v196, s81
	v_cndmask_b32_e64 v196, v196, v240, s[18:19]
	v_cndmask_b32_e64 v221, v200, v241, s[20:21]
	v_max3_f32 v198, v198, v196, v221
	v_cndmask_b32_e64 v222, v200, v242, s[22:23]
	v_cndmask_b32_e64 v223, v200, v243, s[24:25]
	v_max3_f32 v198, v198, v222, v223
	v_mov_b32_e32 v214, v198
	s_nop 1
	v_permlane16_swap_b32_e32 v198, v214
	v_max_f32_e32 v198, v198, v214
	v_mov_b32_e32 v214, v198
	s_nop 1
	v_permlane32_swap_b32_e32 v198, v214
	v_max3_f32 v214, v232, v198, v214
	v_cmp_eq_f32_e64 s[28:29], s81, v214
	v_mul_f32_e32 v224, 0x3e38aa3b, v214
	v_cndmask_b32_e64 v217, v200, v217, s[12:13]
	v_cndmask_b32_e64 v224, v224, 0, s[28:29]
	v_fma_f32 v196, v196, s42, -v224
	v_cndmask_b32_e64 v198, v214, 0, s[28:29]
	v_exp_f32_e32 v225, v196
	v_fma_f32 v196, v199, s42, -v224
	v_sub_f32_e32 v198, v232, v198
	v_exp_f32_e32 v237, v196
	v_fma_f32 v196, v221, s42, -v224
	v_mul_f32_e32 v198, 0x3e38aa3b, v198
	v_exp_f32_e32 v239, v196
	v_fma_f32 v196, v215, s42, -v224
	v_exp_f32_e32 v198, v198
	v_exp_f32_e32 v241, v196
	v_fma_f32 v196, v222, s42, -v224
	v_exp_f32_e32 v243, v196
	v_fma_f32 v196, v220, s42, -v224
	v_exp_f32_e32 v245, v196
	v_fma_f32 v196, v223, s42, -v224
	v_exp_f32_e32 v247, v196
	v_mov_b32_e32 v196, s81
	v_pk_mul_f32 v[162:163], v[162:163], v[198:199] op_sel_hi:[1,0]
	v_pk_mul_f32 v[160:161], v[160:161], v[198:199] op_sel_hi:[1,0]
	v_pk_mul_f32 v[158:159], v[158:159], v[198:199] op_sel_hi:[1,0]
	v_pk_mul_f32 v[156:157], v[156:157], v[198:199] op_sel_hi:[1,0]
	v_pk_mul_f32 v[170:171], v[170:171], v[198:199] op_sel_hi:[1,0]
	v_pk_mul_f32 v[168:169], v[168:169], v[198:199] op_sel_hi:[1,0]
	v_pk_mul_f32 v[178:179], v[178:179], v[198:199] op_sel_hi:[1,0]
	v_pk_mul_f32 v[176:177], v[176:177], v[198:199] op_sel_hi:[1,0]
	v_cndmask_b32_e32 v199, v196, v216, vcc
	v_max3_f32 v196, v199, s81, v217
	v_cndmask_b32_e64 v218, v200, v218, s[14:15]
	v_cndmask_b32_e64 v219, v200, v219, s[16:17]
	v_max3_f32 v215, v196, v218, v219
	v_mov_b32_e32 v196, s81
	v_fma_f32 v197, v197, s42, -v224
	v_cndmask_b32_e64 v224, v196, v228, s[18:19]
	v_cndmask_b32_e64 v228, v200, v229, s[20:21]
	v_max3_f32 v196, v215, v224, v228
	v_cndmask_b32_e64 v229, v200, v230, s[22:23]
	v_cndmask_b32_e64 v230, v200, v231, s[24:25]
	v_max3_f32 v196, v196, v229, v230
	v_mov_b32_e32 v215, v196
	s_nop 1
	v_permlane16_swap_b32_e32 v196, v215
	v_max_f32_e32 v196, v196, v215
	v_mov_b32_e32 v215, v196
	s_nop 1
	v_permlane32_swap_b32_e32 v196, v215
	v_max3_f32 v215, v235, v196, v215
	v_cmp_eq_f32_e32 vcc, s81, v215
	v_exp_f32_e32 v197, v197
	v_cvt_pk_bf16_f32 v221, v241, v245
	v_cndmask_b32_e64 v196, v215, 0, vcc
	v_sub_f32_e32 v196, v235, v196
	v_mul_f32_e32 v196, 0x3e38aa3b, v196
	v_exp_f32_e32 v216, v196
	v_mul_f32_e32 v196, 0x3e38aa3b, v215
	v_cndmask_b32_e64 v231, v196, 0, vcc
	v_fma_f32 v196, v199, s42, -v231
	v_fma_f32 v199, v224, s42, -v231
	v_exp_f32_e32 v224, v199
	v_fma_f32 v199, v217, s42, -v231
	v_exp_f32_e32 v236, v199
	v_fma_f32 v199, v228, s42, -v231
	v_exp_f32_e32 v238, v199
	v_fma_f32 v199, v218, s42, -v231
	v_exp_f32_e32 v196, v196
	v_exp_f32_e32 v240, v199
	v_fma_f32 v199, v229, s42, -v231
	v_exp_f32_e32 v242, v199
	v_fma_f32 v199, v219, s42, -v231
	v_exp_f32_e32 v244, v199
	v_fma_f32 v199, v230, s42, -v231
	v_exp_f32_e32 v246, v199
	v_pk_mul_f32 v[130:131], v[130:131], v[216:217] op_sel_hi:[1,0]
	v_pk_mul_f32 v[128:129], v[128:129], v[216:217] op_sel_hi:[1,0]
	v_pk_mul_f32 v[126:127], v[126:127], v[216:217] op_sel_hi:[1,0]
	v_pk_mul_f32 v[124:125], v[124:125], v[216:217] op_sel_hi:[1,0]
	v_pk_mul_f32 v[138:139], v[138:139], v[216:217] op_sel_hi:[1,0]
	v_pk_mul_f32 v[136:137], v[136:137], v[216:217] op_sel_hi:[1,0]
	v_pk_mul_f32 v[146:147], v[146:147], v[216:217] op_sel_hi:[1,0]
	v_pk_mul_f32 v[144:145], v[144:145], v[216:217] op_sel_hi:[1,0]
	v_mov_b32_e32 v217, v198
	v_pk_add_f32 v[198:199], v[196:197], v[224:225]
	v_pk_add_f32 v[218:219], v[236:237], v[238:239]
	v_cvt_pk_bf16_f32 v220, v197, v237
	v_pk_add_f32 v[198:199], v[218:219], v[198:199]
	v_pk_add_f32 v[218:219], v[240:241], v[242:243]
	v_cvt_pk_bf16_f32 v222, v225, v239
	v_pk_add_f32 v[198:199], v[218:219], v[198:199]
	v_pk_add_f32 v[218:219], v[244:245], v[246:247]
	v_cvt_pk_bf16_f32 v223, v243, v247
	v_pk_add_f32 v[198:199], v[218:219], v[198:199]
	v_cvt_pk_bf16_f32 v218, v224, v238
	v_pk_fma_f32 v[202:203], v[202:203], v[216:217], v[198:199]
	v_cvt_pk_bf16_f32 v216, v196, v236
	v_cvt_pk_bf16_f32 v217, v240, v244
	v_cvt_pk_bf16_f32 v219, v242, v246
	s_setprio 1
	v_add3_u32 v196, v213, v248, v206
	ds_read_b64_tr_b16 v[230:231], v196 offset:31232
	ds_read_b64_tr_b16 v[228:229], v196 offset:28672
	ds_read_b64_tr_b16 v[236:237], v196 offset:28704
	ds_read_b64_tr_b16 v[238:239], v196 offset:31264
	s_waitcnt lgkmcnt(2)
	v_mfma_f32_16x16x32_bf16 v[160:163], v[228:231], v[220:223], v[160:163]
	v_mfma_f32_16x16x32_bf16 v[128:131], v[228:231], v[216:219], v[128:131]
	ds_read_b64_tr_b16 v[228:229], v196 offset:28736
	ds_read_b64_tr_b16 v[230:231], v196 offset:31296
	s_waitcnt lgkmcnt(0)
	v_mfma_f32_16x16x32_bf16 v[168:171], v[228:231], v[220:223], v[168:171]
	v_mfma_f32_16x16x32_bf16 v[136:139], v[228:231], v[216:219], v[136:139]
	ds_read_b64_tr_b16 v[228:229], v196 offset:28768
	ds_read_b64_tr_b16 v[230:231], v196 offset:31328
	v_mfma_f32_16x16x32_bf16 v[156:159], v[236:239], v[220:223], v[156:159]
	v_mfma_f32_16x16x32_bf16 v[124:127], v[236:239], v[216:219], v[124:127]
	s_waitcnt lgkmcnt(0)
	v_mfma_f32_16x16x32_bf16 v[176:179], v[228:231], v[220:223], v[176:179]
	v_mfma_f32_16x16x32_bf16 v[144:147], v[228:231], v[216:219], v[144:147]
	s_setprio 0
	s_mov_b32 s8, 32
	s_andn2_b64 vcc, exec, s[64:65]
	s_mov_b64 s[64:65], 0
	s_cbranch_vccz .LBB0_1281
	s_mov_b64 s[12:13], 0
